# v20 + ssd_sample_unit new_conv_sample copy: 9 loads in flight, one wait, 9 stores (was 5 serial load-wait-store rounds)
# baseline (speedup 1.0000x reference)
.LBB0_669:
	s_or_b64 exec, exec, s[0:1]
	s_cmp_eq_u32 s57, 0
	s_cbranch_scc0 .Lcs_skip
	v_readlane_b32 s58, v254, 32
	v_readlane_b32 s59, v254, 33
	v_readlane_b32 s62, v254, 8
	v_readlane_b32 s63, v254, 9
	v_lshlrev_b32_e32 v12, 1, v158
	v_lshlrev_b32_e32 v13, 2, v158
	s_mul_i32 s4, s92, 0x2600
	s_add_u32 s4, s4, 0x3e00
	s_mul_i32 s6, s29, 0x4800
	s_add_u32 s6, s6, 0xc824800
	s_add_u32 s4, s58, s4
	s_addc_u32 s5, s59, 0
	s_add_u32 s6, s62, s6
	s_addc_u32 s7, s63, 0
	global_load_ushort v2, v12, s[4:5]
	global_load_ushort v3, v12, s[4:5] offset:1024
	global_load_ushort v4, v12, s[4:5] offset:2048
	s_add_u32 s4, s4, 0x2600
	s_addc_u32 s5, s5, 0
	global_load_ushort v5, v12, s[4:5]
	global_load_ushort v6, v12, s[4:5] offset:1024
	global_load_ushort v7, v12, s[4:5] offset:2048
	s_add_u32 s4, s4, 0x2600
	s_addc_u32 s5, s5, 0
	global_load_ushort v8, v12, s[4:5]
	global_load_ushort v9, v12, s[4:5] offset:1024
	global_load_ushort v10, v12, s[4:5] offset:2048
	s_waitcnt vmcnt(0)
	v_lshlrev_b32_e32 v2, 16, v2
	v_lshlrev_b32_e32 v3, 16, v3
	v_lshlrev_b32_e32 v4, 16, v4
	v_lshlrev_b32_e32 v5, 16, v5
	v_lshlrev_b32_e32 v6, 16, v6
	v_lshlrev_b32_e32 v7, 16, v7
	v_lshlrev_b32_e32 v8, 16, v8
	v_lshlrev_b32_e32 v9, 16, v9
	v_lshlrev_b32_e32 v10, 16, v10
	global_store_dword v13, v2, s[6:7] offset:-2048
	global_store_dword v13, v3, s[6:7]
	global_store_dword v13, v4, s[6:7] offset:2048
	s_add_u32 s6, s6, 0x1800
	s_addc_u32 s7, s7, 0
	global_store_dword v13, v5, s[6:7] offset:-2048
	global_store_dword v13, v6, s[6:7]
	global_store_dword v13, v7, s[6:7] offset:2048
	s_add_u32 s6, s6, 0x1800
	s_addc_u32 s7, s7, 0
	global_store_dword v13, v8, s[6:7] offset:-2048
	global_store_dword v13, v9, s[6:7]
	global_store_dword v13, v10, s[6:7] offset:2048
.Lcs_skip:
.LBB0_677:
	s_or_b64 exec, exec, s[0:1]
	v_cmp_gt_i32_e32 vcc, 8, v158
	s_lshl_b32 s4, s57, 3
	s_waitcnt vmcnt(12)
	v_lshl_add_u32 v14, v156, 2, s46
	s_and_saveexec_b64 s[0:1], vcc
	s_cbranch_execz .LBB0_679
	v_readlane_b32 s2, v253, 27
	v_add_u32_e32 v2, s4, v158
	v_ashrrev_i32_e32 v3, 31, v2
	v_mov_b32_e32 v0, s2
	s_waitcnt lgkmcnt(0)
	ds_read_b128 v[4:7], v0
	v_readlane_b32 s2, v254, 35
	v_lshlrev_b64 v[2:3], 2, v[2:3]
	v_readlane_b32 s3, v254, 36
	s_mov_b32 s5, 0xbfb8aa3b
	s_waitcnt lgkmcnt(0)
	v_lshl_add_u64 v[4:5], v[4:5], 0, v[2:3]
	v_lshl_add_u64 v[6:7], v[6:7], 0, v[2:3]
	v_lshl_add_u64 v[2:3], s[2:3], 0, v[2:3]
	s_lshl_b32 s2, s92, 4
	s_mov_b32 s3, s93
	global_load_dword v0, v[6:7], off
	v_lshl_add_u64 v[6:7], s[2:3], 2, v[2:3]
	global_load_dword v4, v[4:5], off
	s_mov_b32 s6, 0x3f2aaaab
	global_load_dword v5, v[6:7], off
	s_mov_b32 s34, 0x3f317218
	s_mov_b32 s7, 0x7f800000
	s_mov_b32 s30, 0x33800000
	s_lshl_b32 s2, s29, 6
	v_lshl_add_u64 v[2:3], s[2:3], 2, v[2:3]
	s_mov_b32 s2, 0x200000
	s_waitcnt vmcnt(2)
	v_mul_f32_e32 v0, 0x3fb8aa3b, v0
	v_exp_f32_e32 v0, v0
	s_waitcnt vmcnt(0)
	v_add_f32_e32 v5, v4, v5
	v_max_f32_e32 v8, 0, v5
	v_mul_f32_e64 v5, |v5|, s5
	v_exp_f32_e32 v5, v5
	s_nop 0
	v_add_f32_e32 v9, 1.0, v5
	v_add_f32_e32 v6, -1.0, v9
	v_sub_f32_e32 v7, v6, v9
	v_add_f32_e32 v7, 1.0, v7
	v_sub_f32_e32 v6, v5, v6
	v_add_f32_e32 v10, v6, v7
	v_frexp_mant_f32_e32 v6, v9
	v_cmp_gt_f32_e32 vcc, s6, v6
	v_cvt_f64_f32_e32 v[6:7], v9
	v_frexp_exp_i32_f64_e32 v6, v[6:7]
	v_subbrev_co_u32_e32 v6, vcc, 0, v6, vcc
	v_sub_u32_e32 v7, 0, v6
	v_ldexp_f32 v9, v9, v7
	v_ldexp_f32 v7, v10, v7
	v_add_f32_e32 v10, -1.0, v9
	v_add_f32_e32 v11, 1.0, v10
	v_sub_f32_e32 v11, v9, v11
	v_add_f32_e32 v11, v7, v11
	v_add_f32_e32 v12, v10, v11
	v_sub_f32_e32 v10, v12, v10
	v_sub_f32_e32 v10, v11, v10
	v_add_f32_e32 v11, 1.0, v9
	v_add_f32_e32 v13, -1.0, v11
	v_sub_f32_e32 v9, v9, v13
	v_add_f32_e32 v7, v7, v9
	v_add_f32_e32 v9, v11, v7
	v_sub_f32_e32 v11, v9, v11
	v_sub_f32_e32 v7, v7, v11
	v_rcp_f32_e32 v11, v9
	v_cvt_f32_i32_e32 v6, v6
	v_cmp_neq_f32_e32 vcc, s7, v5
	v_mul_f32_e32 v13, v12, v11
	v_mul_f32_e32 v15, v9, v13
	v_fma_f32 v16, v13, v9, -v15
	v_fmac_f32_e32 v16, v13, v7
	v_add_f32_e32 v17, v15, v16
	v_sub_f32_e32 v18, v12, v17
	v_sub_f32_e32 v12, v12, v18
	v_sub_f32_e32 v15, v17, v15
	v_sub_f32_e32 v12, v12, v17
	v_add_f32_e32 v10, v10, v12
	v_sub_f32_e32 v12, v15, v16
	v_add_f32_e32 v10, v12, v10
	v_add_f32_e32 v12, v18, v10
	v_mul_f32_e32 v15, v11, v12
	v_mul_f32_e32 v16, v9, v15
	v_fma_f32 v9, v15, v9, -v16
	v_fmac_f32_e32 v9, v15, v7
	v_sub_f32_e32 v7, v18, v12
	v_add_f32_e32 v7, v10, v7
	v_add_f32_e32 v10, v16, v9
	v_sub_f32_e32 v17, v12, v10
	v_sub_f32_e32 v12, v12, v17
	v_sub_f32_e32 v16, v10, v16
	v_sub_f32_e32 v10, v12, v10
	v_add_f32_e32 v7, v7, v10
	v_sub_f32_e32 v9, v16, v9
	v_add_f32_e32 v7, v9, v7
	v_add_f32_e32 v9, v13, v15
	v_add_f32_e32 v7, v17, v7
	v_sub_f32_e32 v10, v9, v13
	v_mul_f32_e32 v7, v11, v7
	v_sub_f32_e32 v10, v15, v10
	v_add_f32_e32 v7, v10, v7
	v_mul_f32_e32 v13, 0x3f317218, v6
	v_add_f32_e32 v10, v9, v7
	v_fma_f32 v15, v6, s34, -v13
	v_mul_f32_e32 v11, v10, v10
	v_fmac_f32_e32 v15, 0xb102e308, v6
	v_sub_f32_e32 v6, v10, v9
	v_fmamk_f32 v12, v11, 0x3e9b6dac, v242
	v_sub_f32_e32 v6, v7, v6
	v_add_f32_e32 v7, v13, v15
	v_fmaak_f32 v12, v11, v12, 0x3f2aaada
	v_sub_f32_e32 v9, v7, v13
	v_ldexp_f32 v13, v10, 1
	v_mul_f32_e32 v10, v10, v11
	v_mul_f32_e32 v10, v10, v12
	v_add_f32_e32 v11, v13, v10
	v_sub_f32_e32 v12, v11, v13
	v_ldexp_f32 v6, v6, 1
	v_sub_f32_e32 v10, v10, v12
	v_add_f32_e32 v6, v6, v10
	v_add_f32_e32 v10, v11, v6
	v_sub_f32_e32 v11, v10, v11
	v_sub_f32_e32 v6, v6, v11
	v_add_f32_e32 v11, v7, v10
	v_sub_f32_e32 v12, v11, v7
	v_sub_f32_e32 v13, v11, v12
	v_sub_f32_e32 v9, v15, v9
	v_sub_f32_e32 v7, v7, v13
	v_sub_f32_e32 v10, v10, v12
	v_add_f32_e32 v7, v10, v7
	v_add_f32_e32 v10, v9, v6
	v_sub_f32_e32 v12, v10, v9
	v_sub_f32_e32 v13, v10, v12
	v_sub_f32_e32 v9, v9, v13
	v_sub_f32_e32 v6, v6, v12
	v_add_f32_e32 v7, v10, v7
	v_add_f32_e32 v6, v6, v9
	v_add_f32_e32 v9, v11, v7
	v_sub_f32_e32 v10, v9, v11
	v_sub_f32_e32 v7, v7, v10
	v_add_f32_e32 v6, v6, v7
	v_add_f32_e32 v6, v9, v6
	v_cndmask_b32_e32 v6, v244, v6, vcc
	v_cmp_ngt_f32_e32 vcc, -1.0, v5
	s_nop 1
	v_cndmask_b32_e32 v6, v245, v6, vcc
	v_cmp_neq_f32_e32 vcc, -1.0, v5
	s_nop 1
	v_cndmask_b32_e32 v6, v252, v6, vcc
	v_cmp_lt_f32_e64 vcc, |v5|, s30
	s_nop 1
	v_cndmask_b32_e32 v5, v6, v5, vcc
	v_add_co_u32_e32 v2, vcc, s2, v2
	v_add_f32_e32 v6, v8, v5
	s_nop 0
	v_addc_co_u32_e32 v3, vcc, 0, v3, vcc
	global_load_dword v5, v[2:3], off offset:64
	v_fma_f32 v8, -v0, v6, 0
	s_waitcnt vmcnt(0)
	v_add_f32_e32 v5, v4, v5
	v_max_f32_e32 v7, 0, v5
	v_mul_f32_e64 v5, |v5|, s5
	v_exp_f32_e32 v5, v5
	s_nop 0
	v_add_f32_e32 v9, 1.0, v5
	v_add_f32_e32 v10, -1.0, v9
	v_sub_f32_e32 v11, v10, v9
	v_add_f32_e32 v11, 1.0, v11
	v_sub_f32_e32 v10, v5, v10
	v_add_f32_e32 v12, v10, v11
	v_frexp_mant_f32_e32 v10, v9
	v_cmp_gt_f32_e32 vcc, s6, v10
	v_cvt_f64_f32_e32 v[10:11], v9
	v_frexp_exp_i32_f64_e32 v10, v[10:11]
	v_subbrev_co_u32_e32 v10, vcc, 0, v10, vcc
	v_sub_u32_e32 v11, 0, v10
	v_ldexp_f32 v9, v9, v11
	v_ldexp_f32 v11, v12, v11
	v_add_f32_e32 v12, -1.0, v9
	v_add_f32_e32 v13, 1.0, v12
	v_sub_f32_e32 v13, v9, v13
	v_add_f32_e32 v13, v11, v13
	v_add_f32_e32 v15, v12, v13
	v_sub_f32_e32 v12, v15, v12
	v_sub_f32_e32 v12, v13, v12
	v_add_f32_e32 v13, 1.0, v9
	v_add_f32_e32 v16, -1.0, v13
	v_sub_f32_e32 v9, v9, v16
	v_add_f32_e32 v9, v11, v9
	v_add_f32_e32 v11, v13, v9
	v_sub_f32_e32 v13, v11, v13
	v_sub_f32_e32 v9, v9, v13
	v_rcp_f32_e32 v13, v11
	v_cvt_f32_i32_e32 v10, v10
	v_cmp_neq_f32_e32 vcc, s7, v5
	v_mul_f32_e32 v16, v15, v13
	v_mul_f32_e32 v17, v11, v16
	v_fma_f32 v18, v16, v11, -v17
	v_fmac_f32_e32 v18, v16, v9
	v_add_f32_e32 v19, v17, v18
	v_sub_f32_e32 v20, v15, v19
	v_sub_f32_e32 v15, v15, v20
	v_sub_f32_e32 v17, v19, v17
	v_sub_f32_e32 v15, v15, v19
	v_add_f32_e32 v12, v12, v15
	v_sub_f32_e32 v15, v17, v18
	v_add_f32_e32 v12, v15, v12
	v_add_f32_e32 v15, v20, v12
	v_mul_f32_e32 v17, v13, v15
	v_mul_f32_e32 v18, v11, v17
	v_fma_f32 v11, v17, v11, -v18
	v_fmac_f32_e32 v11, v17, v9
	v_sub_f32_e32 v9, v20, v15
	v_add_f32_e32 v9, v12, v9
	v_add_f32_e32 v12, v18, v11
	v_sub_f32_e32 v19, v15, v12
	v_sub_f32_e32 v15, v15, v19
	v_sub_f32_e32 v18, v12, v18
	v_sub_f32_e32 v12, v15, v12
	v_add_f32_e32 v9, v9, v12
	v_sub_f32_e32 v11, v18, v11
	v_add_f32_e32 v9, v11, v9
	v_add_f32_e32 v11, v16, v17
	v_add_f32_e32 v9, v19, v9
	v_sub_f32_e32 v12, v11, v16
	v_mul_f32_e32 v9, v13, v9
	v_sub_f32_e32 v12, v17, v12
	v_add_f32_e32 v9, v12, v9
	v_mul_f32_e32 v16, 0x3f317218, v10
	v_add_f32_e32 v12, v11, v9
	v_fma_f32 v17, v10, s34, -v16
	v_mul_f32_e32 v13, v12, v12
	v_fmac_f32_e32 v17, 0xb102e308, v10
	v_sub_f32_e32 v10, v12, v11
	v_fmamk_f32 v15, v13, 0x3e9b6dac, v242
	v_sub_f32_e32 v9, v9, v10
	v_add_f32_e32 v10, v16, v17
	v_fmaak_f32 v15, v13, v15, 0x3f2aaada
	v_sub_f32_e32 v11, v10, v16
	v_ldexp_f32 v16, v12, 1
	v_mul_f32_e32 v12, v12, v13
	v_mul_f32_e32 v12, v12, v15
	v_add_f32_e32 v13, v16, v12
	v_sub_f32_e32 v15, v13, v16
	v_ldexp_f32 v9, v9, 1
	v_sub_f32_e32 v12, v12, v15
	v_add_f32_e32 v9, v9, v12
	v_add_f32_e32 v12, v13, v9
	v_sub_f32_e32 v13, v12, v13
	v_sub_f32_e32 v9, v9, v13
	v_add_f32_e32 v13, v10, v12
	v_sub_f32_e32 v15, v13, v10
	v_sub_f32_e32 v16, v13, v15
	v_sub_f32_e32 v11, v17, v11
	v_sub_f32_e32 v10, v10, v16
	v_sub_f32_e32 v12, v12, v15
	v_add_f32_e32 v10, v12, v10
	v_add_f32_e32 v12, v11, v9
	v_sub_f32_e32 v15, v12, v11
	v_sub_f32_e32 v16, v12, v15
	v_sub_f32_e32 v11, v11, v16
	v_sub_f32_e32 v9, v9, v15
	v_add_f32_e32 v10, v12, v10
	v_add_f32_e32 v9, v9, v11
	v_add_f32_e32 v11, v13, v10
	v_sub_f32_e32 v12, v11, v13
	v_sub_f32_e32 v10, v10, v12
	v_add_f32_e32 v9, v9, v10
	v_add_f32_e32 v9, v11, v9
	v_cndmask_b32_e32 v9, v244, v9, vcc
	v_cmp_ngt_f32_e32 vcc, -1.0, v5
	s_nop 1
	v_cndmask_b32_e32 v9, v245, v9, vcc
	v_cmp_neq_f32_e32 vcc, -1.0, v5
	s_nop 1
	v_cndmask_b32_e32 v9, v252, v9, vcc
	v_cmp_lt_f32_e64 vcc, |v5|, s30
	s_nop 1
	v_cndmask_b32_e32 v5, v9, v5, vcc
	v_add_f32_e32 v9, v7, v5
	v_add_u32_e32 v5, 0x3000, v14
	v_fma_f32 v7, -v0, v9, v8
	ds_write2_b32 v5, v6, v9 offset1:8
	ds_write2_b32 v5, v8, v7 offset0:32 offset1:40
	global_load_dword v6, v[2:3], off offset:128
	s_waitcnt vmcnt(0)
	v_add_f32_e32 v6, v4, v6
	v_max_f32_e32 v10, 0, v6
	v_mul_f32_e64 v6, |v6|, s5
	global_load_dword v2, v[2:3], off offset:192
	v_exp_f32_e32 v6, v6
	s_waitcnt vmcnt(0)
	v_add_f32_e32 v2, v4, v2
	v_add_f32_e32 v11, 1.0, v6
	v_add_f32_e32 v8, -1.0, v11
	v_sub_f32_e32 v9, v8, v11
	v_add_f32_e32 v9, 1.0, v9
	v_sub_f32_e32 v8, v6, v8
	v_add_f32_e32 v12, v8, v9
	v_frexp_mant_f32_e32 v8, v11
	v_cmp_gt_f32_e32 vcc, s6, v8
	v_cvt_f64_f32_e32 v[8:9], v11
	v_frexp_exp_i32_f64_e32 v8, v[8:9]
	v_subbrev_co_u32_e32 v8, vcc, 0, v8, vcc
	v_sub_u32_e32 v9, 0, v8
	v_ldexp_f32 v11, v11, v9
	v_ldexp_f32 v9, v12, v9
	v_add_f32_e32 v12, -1.0, v11
	v_add_f32_e32 v13, 1.0, v12
	v_sub_f32_e32 v13, v11, v13
	v_add_f32_e32 v13, v9, v13
	v_add_f32_e32 v15, v12, v13
	v_sub_f32_e32 v12, v15, v12
	v_sub_f32_e32 v12, v13, v12
	v_add_f32_e32 v13, 1.0, v11
	v_add_f32_e32 v16, -1.0, v13
	v_sub_f32_e32 v11, v11, v16
	v_add_f32_e32 v9, v9, v11
	v_add_f32_e32 v11, v13, v9
	v_sub_f32_e32 v13, v11, v13
	v_sub_f32_e32 v9, v9, v13
	v_rcp_f32_e32 v13, v11
	v_cvt_f32_i32_e32 v8, v8
	v_cmp_neq_f32_e32 vcc, s7, v6
	v_max_f32_e32 v4, 0, v2
	v_mul_f32_e32 v16, v15, v13
	v_mul_f32_e32 v17, v11, v16
	v_fma_f32 v18, v16, v11, -v17
	v_fmac_f32_e32 v18, v16, v9
	v_add_f32_e32 v19, v17, v18
	v_sub_f32_e32 v20, v15, v19
	v_sub_f32_e32 v15, v15, v20
	v_sub_f32_e32 v17, v19, v17
	v_sub_f32_e32 v15, v15, v19
	v_add_f32_e32 v12, v12, v15
	v_sub_f32_e32 v15, v17, v18
	v_add_f32_e32 v12, v15, v12
	v_add_f32_e32 v15, v20, v12
	v_mul_f32_e32 v17, v13, v15
	v_mul_f32_e32 v18, v11, v17
	v_fma_f32 v11, v17, v11, -v18
	v_fmac_f32_e32 v11, v17, v9
	v_sub_f32_e32 v9, v20, v15
	v_add_f32_e32 v9, v12, v9
	v_add_f32_e32 v12, v18, v11
	v_sub_f32_e32 v19, v15, v12
	v_sub_f32_e32 v15, v15, v19
	v_sub_f32_e32 v18, v12, v18
	v_sub_f32_e32 v12, v15, v12
	v_add_f32_e32 v9, v9, v12
	v_sub_f32_e32 v11, v18, v11
	v_add_f32_e32 v9, v11, v9
	v_add_f32_e32 v11, v16, v17
	v_add_f32_e32 v9, v19, v9
	v_sub_f32_e32 v12, v11, v16
	v_mul_f32_e32 v9, v13, v9
	v_sub_f32_e32 v12, v17, v12
	v_add_f32_e32 v9, v12, v9
	v_mul_f32_e32 v16, 0x3f317218, v8
	v_add_f32_e32 v12, v11, v9
	v_fma_f32 v17, v8, s34, -v16
	v_mul_f32_e32 v13, v12, v12
	v_fmac_f32_e32 v17, 0xb102e308, v8
	v_sub_f32_e32 v8, v12, v11
	v_fmamk_f32 v15, v13, 0x3e9b6dac, v242
	v_sub_f32_e32 v8, v9, v8
	v_add_f32_e32 v9, v16, v17
	v_fmaak_f32 v15, v13, v15, 0x3f2aaada
	v_sub_f32_e32 v11, v9, v16
	v_ldexp_f32 v16, v12, 1
	v_mul_f32_e32 v12, v12, v13
	v_mul_f32_e32 v12, v12, v15
	v_add_f32_e32 v13, v16, v12
	v_sub_f32_e32 v15, v13, v16
	v_ldexp_f32 v8, v8, 1
	v_sub_f32_e32 v12, v12, v15
	v_add_f32_e32 v8, v8, v12
	v_add_f32_e32 v12, v13, v8
	v_sub_f32_e32 v13, v12, v13
	v_sub_f32_e32 v8, v8, v13
	v_add_f32_e32 v13, v9, v12
	v_sub_f32_e32 v15, v13, v9
	v_sub_f32_e32 v16, v13, v15
	v_sub_f32_e32 v11, v17, v11
	v_sub_f32_e32 v9, v9, v16
	v_sub_f32_e32 v12, v12, v15
	v_add_f32_e32 v9, v12, v9
	v_add_f32_e32 v12, v11, v8
	v_sub_f32_e32 v15, v12, v11
	v_sub_f32_e32 v16, v12, v15
	v_sub_f32_e32 v11, v11, v16
	v_sub_f32_e32 v8, v8, v15
	v_add_f32_e32 v9, v12, v9
	v_add_f32_e32 v8, v8, v11
	v_add_f32_e32 v11, v13, v9
	v_sub_f32_e32 v12, v11, v13
	v_sub_f32_e32 v9, v9, v12
	v_add_f32_e32 v8, v8, v9
	v_add_f32_e32 v8, v11, v8
	v_cndmask_b32_e32 v8, v244, v8, vcc
	v_cmp_ngt_f32_e32 vcc, -1.0, v6
	v_mul_f32_e64 v2, |v2|, s5
	s_nop 0
	v_cndmask_b32_e32 v8, v245, v8, vcc
	v_cmp_neq_f32_e32 vcc, -1.0, v6
	s_nop 1
	v_cndmask_b32_e32 v8, v252, v8, vcc
	v_cmp_lt_f32_e64 vcc, |v6|, s30
	s_nop 1
	v_cndmask_b32_e32 v6, v8, v6, vcc
	v_exp_f32_e32 v8, v2
	v_add_f32_e32 v6, v10, v6
	v_fma_f32 v7, -v0, v6, v7
	v_add_f32_e32 v9, 1.0, v8
	v_add_f32_e32 v2, -1.0, v9
	v_sub_f32_e32 v3, v2, v9
	v_add_f32_e32 v3, 1.0, v3
	v_sub_f32_e32 v2, v8, v2
	v_add_f32_e32 v10, v2, v3
	v_frexp_mant_f32_e32 v2, v9
	v_cmp_gt_f32_e32 vcc, s6, v2
	v_cvt_f64_f32_e32 v[2:3], v9
	v_frexp_exp_i32_f64_e32 v2, v[2:3]
	v_subbrev_co_u32_e32 v2, vcc, 0, v2, vcc
	v_sub_u32_e32 v3, 0, v2
	v_ldexp_f32 v9, v9, v3
	v_ldexp_f32 v3, v10, v3
	v_add_f32_e32 v10, -1.0, v9
	v_add_f32_e32 v11, 1.0, v10
	v_sub_f32_e32 v11, v9, v11
	v_add_f32_e32 v11, v3, v11
	v_add_f32_e32 v12, v10, v11
	v_sub_f32_e32 v10, v12, v10
	v_sub_f32_e32 v10, v11, v10
	v_add_f32_e32 v11, 1.0, v9
	v_add_f32_e32 v13, -1.0, v11
	v_sub_f32_e32 v9, v9, v13
	v_add_f32_e32 v3, v3, v9
	v_add_f32_e32 v9, v11, v3
	v_sub_f32_e32 v11, v9, v11
	v_sub_f32_e32 v3, v3, v11
	v_rcp_f32_e32 v11, v9
	v_cvt_f32_i32_e32 v2, v2
	v_cmp_neq_f32_e32 vcc, s7, v8
	v_mul_f32_e32 v13, v12, v11
	v_mul_f32_e32 v15, v9, v13
	v_fma_f32 v16, v13, v9, -v15
	v_fmac_f32_e32 v16, v13, v3
	v_add_f32_e32 v17, v15, v16
	v_sub_f32_e32 v18, v12, v17
	v_sub_f32_e32 v12, v12, v18
	v_sub_f32_e32 v15, v17, v15
	v_sub_f32_e32 v12, v12, v17
	v_add_f32_e32 v10, v10, v12
	v_sub_f32_e32 v12, v15, v16
	v_add_f32_e32 v10, v12, v10
	v_add_f32_e32 v12, v18, v10
	v_mul_f32_e32 v15, v11, v12
	v_mul_f32_e32 v16, v9, v15
	v_fma_f32 v9, v15, v9, -v16
	v_fmac_f32_e32 v9, v15, v3
	v_sub_f32_e32 v3, v18, v12
	v_add_f32_e32 v3, v10, v3
	v_add_f32_e32 v10, v16, v9
	v_sub_f32_e32 v17, v12, v10
	v_sub_f32_e32 v12, v12, v17
	v_sub_f32_e32 v16, v10, v16
	v_sub_f32_e32 v10, v12, v10
	v_add_f32_e32 v3, v3, v10
	v_sub_f32_e32 v9, v16, v9
	v_add_f32_e32 v3, v9, v3
	v_add_f32_e32 v9, v13, v15
	v_add_f32_e32 v3, v17, v3
	v_sub_f32_e32 v10, v9, v13
	v_mul_f32_e32 v3, v11, v3
	v_sub_f32_e32 v10, v15, v10
	v_add_f32_e32 v3, v10, v3
	v_mul_f32_e32 v13, 0x3f317218, v2
	v_add_f32_e32 v10, v9, v3
	v_fma_f32 v15, v2, s34, -v13
	v_mul_f32_e32 v11, v10, v10
	v_fmac_f32_e32 v15, 0xb102e308, v2
	v_sub_f32_e32 v2, v10, v9
	v_fmamk_f32 v12, v11, 0x3e9b6dac, v242
	v_sub_f32_e32 v2, v3, v2
	v_add_f32_e32 v3, v13, v15
	v_fmaak_f32 v12, v11, v12, 0x3f2aaada
	v_sub_f32_e32 v9, v3, v13
	v_ldexp_f32 v13, v10, 1
	v_mul_f32_e32 v10, v10, v11
	v_mul_f32_e32 v10, v10, v12
	v_add_f32_e32 v11, v13, v10
	v_sub_f32_e32 v12, v11, v13
	v_ldexp_f32 v2, v2, 1
	v_sub_f32_e32 v10, v10, v12
	v_add_f32_e32 v2, v2, v10
	v_add_f32_e32 v10, v11, v2
	v_sub_f32_e32 v11, v10, v11
	v_sub_f32_e32 v2, v2, v11
	v_add_f32_e32 v11, v3, v10
	v_sub_f32_e32 v12, v11, v3
	v_sub_f32_e32 v13, v11, v12
	v_sub_f32_e32 v9, v15, v9
	v_sub_f32_e32 v3, v3, v13
	v_sub_f32_e32 v10, v10, v12
	v_add_f32_e32 v3, v10, v3
	v_add_f32_e32 v10, v9, v2
	v_sub_f32_e32 v12, v10, v9
	v_sub_f32_e32 v13, v10, v12
	v_sub_f32_e32 v9, v9, v13
	v_sub_f32_e32 v2, v2, v12
	v_add_f32_e32 v3, v10, v3
	v_add_f32_e32 v2, v2, v9
	v_add_f32_e32 v9, v11, v3
	v_sub_f32_e32 v10, v9, v11
	v_sub_f32_e32 v3, v3, v10
	v_add_f32_e32 v2, v2, v3
	v_add_f32_e32 v2, v9, v2
	v_cndmask_b32_e32 v2, v244, v2, vcc
	v_cmp_ngt_f32_e32 vcc, -1.0, v8
	s_nop 1
	v_cndmask_b32_e32 v2, v245, v2, vcc
	v_cmp_neq_f32_e32 vcc, -1.0, v8
	s_nop 1
	v_cndmask_b32_e32 v2, v252, v2, vcc
	v_cmp_lt_f32_e64 vcc, |v8|, s30
	s_nop 1
	v_cndmask_b32_e32 v2, v2, v8, vcc
	v_add_f32_e32 v2, v4, v2
	v_fma_f32 v0, -v0, v2, v7
	ds_write2_b32 v5, v6, v2 offset0:16 offset1:24
	ds_write2_b32 v5, v7, v0 offset0:48 offset1:56
